# hand-written final rms-norm phase: gain vector preloaded into registers, next row's delta loads issued a full row ahead
# baseline (speedup 1.0000x reference)
.LBB0_833:
	s_cmp_lt_i32 s62, 15
	s_cselect_b64 s[0:1], -1, 0
	s_cmp_gt_i32 s63, 14
	s_cselect_b64 s[2:3], -1, 0
	s_and_b64 s[0:1], s[0:1], s[2:3]
	s_and_b64 vcc, exec, s[0:1]
	s_cbranch_vccz .LBB0_837
	v_readlane_b32 s1, v253, 5
	v_readfirstlane_b32 s0, v0
	s_ashr_i32 s0, s0, 6
	s_add_i32 s2, s0, s1
	s_cmpk_gt_i32 s2, 0x3fff
	s_cbranch_scc1 .LBB0_837
	s_load_dwordx2 s[48:49], s[70:71], 0xd0
	s_load_dwordx4 s[4:7], s[70:71], 0xd8
	v_and_b32_e32 v228, 63, v0
	v_lshlrev_b32_e32 v236, 4, v228
	v_add_u32_e32 v237, 0x1000, v236
	v_add_u32_e32 v238, 0x2000, v236
	v_add_u32_e32 v239, 0x3000, v236
	v_lshlrev_b32_e32 v240, 3, v228
	v_add_u32_e32 v241, 0x1000, v240
	s_mov_b32 s40, s2
	s_waitcnt vmcnt(0) lgkmcnt(0)
	s_add_u32 s8, s6, 0x30a38000
	s_addc_u32 s9, s7, 0
	s_add_u32 s10, s8, 0x8000000
	s_addc_u32 s11, s9, 0
	global_load_dwordx4 v[2:5], v236, s[48:49]
	global_load_dwordx4 v[6:9], v236, s[48:49] offset:1024
	global_load_dwordx4 v[10:13], v236, s[48:49] offset:2048
	global_load_dwordx4 v[14:17], v236, s[48:49] offset:3072
	global_load_dwordx4 v[18:21], v237, s[48:49]
	global_load_dwordx4 v[22:25], v237, s[48:49] offset:1024
	global_load_dwordx4 v[26:29], v237, s[48:49] offset:2048
	global_load_dwordx4 v[30:33], v237, s[48:49] offset:3072
	global_load_dwordx4 v[34:37], v238, s[48:49]
	global_load_dwordx4 v[38:41], v238, s[48:49] offset:1024
	global_load_dwordx4 v[42:45], v238, s[48:49] offset:2048
	global_load_dwordx4 v[46:49], v238, s[48:49] offset:3072
	global_load_dwordx4 v[50:53], v239, s[48:49]
	global_load_dwordx4 v[54:57], v239, s[48:49] offset:1024
	global_load_dwordx4 v[58:61], v239, s[48:49] offset:2048
	global_load_dwordx4 v[62:65], v239, s[48:49] offset:3072
	s_lshl_b32 s41, s40, 13
	s_add_u32 s32, s8, s41
	s_addc_u32 s33, s9, 0
	s_add_u32 s34, s10, s41
	s_addc_u32 s35, s11, 0
	global_load_dwordx2 v[66:67], v240, s[32:33]
	global_load_dwordx2 v[68:69], v240, s[34:35]
	global_load_dwordx2 v[70:71], v240, s[32:33] offset:512
	global_load_dwordx2 v[72:73], v240, s[34:35] offset:512
	global_load_dwordx2 v[74:75], v240, s[32:33] offset:1024
	global_load_dwordx2 v[76:77], v240, s[34:35] offset:1024
	global_load_dwordx2 v[78:79], v240, s[32:33] offset:1536
	global_load_dwordx2 v[80:81], v240, s[34:35] offset:1536
	global_load_dwordx2 v[82:83], v240, s[32:33] offset:2048
	global_load_dwordx2 v[84:85], v240, s[34:35] offset:2048
	global_load_dwordx2 v[86:87], v240, s[32:33] offset:2560
	global_load_dwordx2 v[88:89], v240, s[34:35] offset:2560
	global_load_dwordx2 v[90:91], v240, s[32:33] offset:3072
	global_load_dwordx2 v[92:93], v240, s[34:35] offset:3072
	global_load_dwordx2 v[94:95], v240, s[32:33] offset:3584
	global_load_dwordx2 v[96:97], v240, s[34:35] offset:3584
	global_load_dwordx2 v[98:99], v241, s[32:33]
	global_load_dwordx2 v[100:101], v241, s[34:35]
	global_load_dwordx2 v[102:103], v241, s[32:33] offset:512
	global_load_dwordx2 v[104:105], v241, s[34:35] offset:512
	global_load_dwordx2 v[106:107], v241, s[32:33] offset:1024
	global_load_dwordx2 v[108:109], v241, s[34:35] offset:1024
	global_load_dwordx2 v[110:111], v241, s[32:33] offset:1536
	global_load_dwordx2 v[112:113], v241, s[34:35] offset:1536
	global_load_dwordx2 v[114:115], v241, s[32:33] offset:2048
	global_load_dwordx2 v[116:117], v241, s[34:35] offset:2048
	global_load_dwordx2 v[118:119], v241, s[32:33] offset:2560
	global_load_dwordx2 v[120:121], v241, s[34:35] offset:2560
	global_load_dwordx2 v[122:123], v241, s[32:33] offset:3072
	global_load_dwordx2 v[124:125], v241, s[34:35] offset:3072
	global_load_dwordx2 v[126:127], v241, s[32:33] offset:3584
	global_load_dwordx2 v[128:129], v241, s[34:35] offset:3584
	s_waitcnt vmcnt(32)
	s_add_i32 s38, s40, s96
	s_cmpk_gt_i32 s38, 0x3fff
	s_cselect_b32 s39, 1, 0
	s_cselect_b32 s38, s40, s38
	s_lshl_b32 s41, s38, 13
	s_add_u32 s32, s8, s41
	s_addc_u32 s33, s9, 0
	s_add_u32 s34, s10, s41
	s_addc_u32 s35, s11, 0
	s_lshl_b32 s41, s40, 14
	s_add_u32 s36, s4, s41
	s_addc_u32 s37, s5, 0
	s_waitcnt vmcnt(30)
	v_lshlrev_b32_e32 v228, 16, v66
	v_and_b32_e32 v229, 0xffff0000, v66
	v_lshlrev_b32_e32 v230, 16, v67
	v_and_b32_e32 v231, 0xffff0000, v67
	v_lshlrev_b32_e32 v66, 16, v68
	v_and_b32_e32 v67, 0xffff0000, v68
	v_lshlrev_b32_e32 v68, 16, v69
	v_and_b32_e32 v69, 0xffff0000, v69
	v_pk_add_f32 v[66:67], v[228:229], v[66:67]
	v_pk_add_f32 v[68:69], v[230:231], v[68:69]
	v_pk_mul_f32 v[232:233], v[66:67], v[66:67]
	v_pk_fma_f32 v[232:233], v[68:69], v[68:69], v[232:233]
	global_load_dwordx2 v[130:131], v240, s[32:33]
	global_load_dwordx2 v[132:133], v240, s[34:35]
	s_waitcnt vmcnt(30)
	v_lshlrev_b32_e32 v228, 16, v70
	v_and_b32_e32 v229, 0xffff0000, v70
	v_lshlrev_b32_e32 v230, 16, v71
	v_and_b32_e32 v231, 0xffff0000, v71
	v_lshlrev_b32_e32 v70, 16, v72
	v_and_b32_e32 v71, 0xffff0000, v72
	v_lshlrev_b32_e32 v72, 16, v73
	v_and_b32_e32 v73, 0xffff0000, v73
	v_pk_add_f32 v[70:71], v[228:229], v[70:71]
	v_pk_add_f32 v[72:73], v[230:231], v[72:73]
	v_pk_fma_f32 v[232:233], v[70:71], v[70:71], v[232:233]
	v_pk_fma_f32 v[232:233], v[72:73], v[72:73], v[232:233]
	global_load_dwordx2 v[134:135], v240, s[32:33] offset:512
	global_load_dwordx2 v[136:137], v240, s[34:35] offset:512
	s_waitcnt vmcnt(30)
	v_lshlrev_b32_e32 v228, 16, v74
	v_and_b32_e32 v229, 0xffff0000, v74
	v_lshlrev_b32_e32 v230, 16, v75
	v_and_b32_e32 v231, 0xffff0000, v75
	v_lshlrev_b32_e32 v74, 16, v76
	v_and_b32_e32 v75, 0xffff0000, v76
	v_lshlrev_b32_e32 v76, 16, v77
	v_and_b32_e32 v77, 0xffff0000, v77
	v_pk_add_f32 v[74:75], v[228:229], v[74:75]
	v_pk_add_f32 v[76:77], v[230:231], v[76:77]
	v_pk_fma_f32 v[232:233], v[74:75], v[74:75], v[232:233]
	v_pk_fma_f32 v[232:233], v[76:77], v[76:77], v[232:233]
	global_load_dwordx2 v[138:139], v240, s[32:33] offset:1024
	global_load_dwordx2 v[140:141], v240, s[34:35] offset:1024
	s_waitcnt vmcnt(30)
	v_lshlrev_b32_e32 v228, 16, v78
	v_and_b32_e32 v229, 0xffff0000, v78
	v_lshlrev_b32_e32 v230, 16, v79
	v_and_b32_e32 v231, 0xffff0000, v79
	v_lshlrev_b32_e32 v78, 16, v80
	v_and_b32_e32 v79, 0xffff0000, v80
	v_lshlrev_b32_e32 v80, 16, v81
	v_and_b32_e32 v81, 0xffff0000, v81
	v_pk_add_f32 v[78:79], v[228:229], v[78:79]
	v_pk_add_f32 v[80:81], v[230:231], v[80:81]
	v_pk_fma_f32 v[232:233], v[78:79], v[78:79], v[232:233]
	v_pk_fma_f32 v[232:233], v[80:81], v[80:81], v[232:233]
	global_load_dwordx2 v[142:143], v240, s[32:33] offset:1536
	global_load_dwordx2 v[144:145], v240, s[34:35] offset:1536
	s_waitcnt vmcnt(30)
	v_lshlrev_b32_e32 v228, 16, v82
	v_and_b32_e32 v229, 0xffff0000, v82
	v_lshlrev_b32_e32 v230, 16, v83
	v_and_b32_e32 v231, 0xffff0000, v83
	v_lshlrev_b32_e32 v82, 16, v84
	v_and_b32_e32 v83, 0xffff0000, v84
	v_lshlrev_b32_e32 v84, 16, v85
	v_and_b32_e32 v85, 0xffff0000, v85
	v_pk_add_f32 v[82:83], v[228:229], v[82:83]
	v_pk_add_f32 v[84:85], v[230:231], v[84:85]
	v_pk_fma_f32 v[232:233], v[82:83], v[82:83], v[232:233]
	v_pk_fma_f32 v[232:233], v[84:85], v[84:85], v[232:233]
	global_load_dwordx2 v[146:147], v240, s[32:33] offset:2048
	global_load_dwordx2 v[148:149], v240, s[34:35] offset:2048
	s_waitcnt vmcnt(30)
	v_lshlrev_b32_e32 v228, 16, v86
	v_and_b32_e32 v229, 0xffff0000, v86
	v_lshlrev_b32_e32 v230, 16, v87
	v_and_b32_e32 v231, 0xffff0000, v87
	v_lshlrev_b32_e32 v86, 16, v88
	v_and_b32_e32 v87, 0xffff0000, v88
	v_lshlrev_b32_e32 v88, 16, v89
	v_and_b32_e32 v89, 0xffff0000, v89
	v_pk_add_f32 v[86:87], v[228:229], v[86:87]
	v_pk_add_f32 v[88:89], v[230:231], v[88:89]
	v_pk_fma_f32 v[232:233], v[86:87], v[86:87], v[232:233]
	v_pk_fma_f32 v[232:233], v[88:89], v[88:89], v[232:233]
	global_load_dwordx2 v[150:151], v240, s[32:33] offset:2560
	global_load_dwordx2 v[152:153], v240, s[34:35] offset:2560
	s_waitcnt vmcnt(30)
	v_lshlrev_b32_e32 v228, 16, v90
	v_and_b32_e32 v229, 0xffff0000, v90
	v_lshlrev_b32_e32 v230, 16, v91
	v_and_b32_e32 v231, 0xffff0000, v91
	v_lshlrev_b32_e32 v90, 16, v92
	v_and_b32_e32 v91, 0xffff0000, v92
	v_lshlrev_b32_e32 v92, 16, v93
	v_and_b32_e32 v93, 0xffff0000, v93
	v_pk_add_f32 v[90:91], v[228:229], v[90:91]
	v_pk_add_f32 v[92:93], v[230:231], v[92:93]
	v_pk_fma_f32 v[232:233], v[90:91], v[90:91], v[232:233]
	v_pk_fma_f32 v[232:233], v[92:93], v[92:93], v[232:233]
	global_load_dwordx2 v[154:155], v240, s[32:33] offset:3072
	global_load_dwordx2 v[156:157], v240, s[34:35] offset:3072
	s_waitcnt vmcnt(30)
	v_lshlrev_b32_e32 v228, 16, v94
	v_and_b32_e32 v229, 0xffff0000, v94
	v_lshlrev_b32_e32 v230, 16, v95
	v_and_b32_e32 v231, 0xffff0000, v95
	v_lshlrev_b32_e32 v94, 16, v96
	v_and_b32_e32 v95, 0xffff0000, v96
	v_lshlrev_b32_e32 v96, 16, v97
	v_and_b32_e32 v97, 0xffff0000, v97
	v_pk_add_f32 v[94:95], v[228:229], v[94:95]
	v_pk_add_f32 v[96:97], v[230:231], v[96:97]
	v_pk_fma_f32 v[232:233], v[94:95], v[94:95], v[232:233]
	v_pk_fma_f32 v[232:233], v[96:97], v[96:97], v[232:233]
	global_load_dwordx2 v[158:159], v240, s[32:33] offset:3584
	global_load_dwordx2 v[160:161], v240, s[34:35] offset:3584
	s_waitcnt vmcnt(30)
	v_lshlrev_b32_e32 v228, 16, v98
	v_and_b32_e32 v229, 0xffff0000, v98
	v_lshlrev_b32_e32 v230, 16, v99
	v_and_b32_e32 v231, 0xffff0000, v99
	v_lshlrev_b32_e32 v98, 16, v100
	v_and_b32_e32 v99, 0xffff0000, v100
	v_lshlrev_b32_e32 v100, 16, v101
	v_and_b32_e32 v101, 0xffff0000, v101
	v_pk_add_f32 v[98:99], v[228:229], v[98:99]
	v_pk_add_f32 v[100:101], v[230:231], v[100:101]
	v_pk_fma_f32 v[232:233], v[98:99], v[98:99], v[232:233]
	v_pk_fma_f32 v[232:233], v[100:101], v[100:101], v[232:233]
	global_load_dwordx2 v[162:163], v241, s[32:33]
	global_load_dwordx2 v[164:165], v241, s[34:35]
	s_waitcnt vmcnt(30)
	v_lshlrev_b32_e32 v228, 16, v102
	v_and_b32_e32 v229, 0xffff0000, v102
	v_lshlrev_b32_e32 v230, 16, v103
	v_and_b32_e32 v231, 0xffff0000, v103
	v_lshlrev_b32_e32 v102, 16, v104
	v_and_b32_e32 v103, 0xffff0000, v104
	v_lshlrev_b32_e32 v104, 16, v105
	v_and_b32_e32 v105, 0xffff0000, v105
	v_pk_add_f32 v[102:103], v[228:229], v[102:103]
	v_pk_add_f32 v[104:105], v[230:231], v[104:105]
	v_pk_fma_f32 v[232:233], v[102:103], v[102:103], v[232:233]
	v_pk_fma_f32 v[232:233], v[104:105], v[104:105], v[232:233]
	global_load_dwordx2 v[166:167], v241, s[32:33] offset:512
	global_load_dwordx2 v[168:169], v241, s[34:35] offset:512
	s_waitcnt vmcnt(30)
	v_lshlrev_b32_e32 v228, 16, v106
	v_and_b32_e32 v229, 0xffff0000, v106
	v_lshlrev_b32_e32 v230, 16, v107
	v_and_b32_e32 v231, 0xffff0000, v107
	v_lshlrev_b32_e32 v106, 16, v108
	v_and_b32_e32 v107, 0xffff0000, v108
	v_lshlrev_b32_e32 v108, 16, v109
	v_and_b32_e32 v109, 0xffff0000, v109
	v_pk_add_f32 v[106:107], v[228:229], v[106:107]
	v_pk_add_f32 v[108:109], v[230:231], v[108:109]
	v_pk_fma_f32 v[232:233], v[106:107], v[106:107], v[232:233]
	v_pk_fma_f32 v[232:233], v[108:109], v[108:109], v[232:233]
	global_load_dwordx2 v[170:171], v241, s[32:33] offset:1024
	global_load_dwordx2 v[172:173], v241, s[34:35] offset:1024
	s_waitcnt vmcnt(30)
	v_lshlrev_b32_e32 v228, 16, v110
	v_and_b32_e32 v229, 0xffff0000, v110
	v_lshlrev_b32_e32 v230, 16, v111
	v_and_b32_e32 v231, 0xffff0000, v111
	v_lshlrev_b32_e32 v110, 16, v112
	v_and_b32_e32 v111, 0xffff0000, v112
	v_lshlrev_b32_e32 v112, 16, v113
	v_and_b32_e32 v113, 0xffff0000, v113
	v_pk_add_f32 v[110:111], v[228:229], v[110:111]
	v_pk_add_f32 v[112:113], v[230:231], v[112:113]
	v_pk_fma_f32 v[232:233], v[110:111], v[110:111], v[232:233]
	v_pk_fma_f32 v[232:233], v[112:113], v[112:113], v[232:233]
	global_load_dwordx2 v[174:175], v241, s[32:33] offset:1536
	global_load_dwordx2 v[176:177], v241, s[34:35] offset:1536
	s_waitcnt vmcnt(30)
	v_lshlrev_b32_e32 v228, 16, v114
	v_and_b32_e32 v229, 0xffff0000, v114
	v_lshlrev_b32_e32 v230, 16, v115
	v_and_b32_e32 v231, 0xffff0000, v115
	v_lshlrev_b32_e32 v114, 16, v116
	v_and_b32_e32 v115, 0xffff0000, v116
	v_lshlrev_b32_e32 v116, 16, v117
	v_and_b32_e32 v117, 0xffff0000, v117
	v_pk_add_f32 v[114:115], v[228:229], v[114:115]
	v_pk_add_f32 v[116:117], v[230:231], v[116:117]
	v_pk_fma_f32 v[232:233], v[114:115], v[114:115], v[232:233]
	v_pk_fma_f32 v[232:233], v[116:117], v[116:117], v[232:233]
	global_load_dwordx2 v[178:179], v241, s[32:33] offset:2048
	global_load_dwordx2 v[180:181], v241, s[34:35] offset:2048
	s_waitcnt vmcnt(30)
	v_lshlrev_b32_e32 v228, 16, v118
	v_and_b32_e32 v229, 0xffff0000, v118
	v_lshlrev_b32_e32 v230, 16, v119
	v_and_b32_e32 v231, 0xffff0000, v119
	v_lshlrev_b32_e32 v118, 16, v120
	v_and_b32_e32 v119, 0xffff0000, v120
	v_lshlrev_b32_e32 v120, 16, v121
	v_and_b32_e32 v121, 0xffff0000, v121
	v_pk_add_f32 v[118:119], v[228:229], v[118:119]
	v_pk_add_f32 v[120:121], v[230:231], v[120:121]
	v_pk_fma_f32 v[232:233], v[118:119], v[118:119], v[232:233]
	v_pk_fma_f32 v[232:233], v[120:121], v[120:121], v[232:233]
	global_load_dwordx2 v[182:183], v241, s[32:33] offset:2560
	global_load_dwordx2 v[184:185], v241, s[34:35] offset:2560
	s_waitcnt vmcnt(30)
	v_lshlrev_b32_e32 v228, 16, v122
	v_and_b32_e32 v229, 0xffff0000, v122
	v_lshlrev_b32_e32 v230, 16, v123
	v_and_b32_e32 v231, 0xffff0000, v123
	v_lshlrev_b32_e32 v122, 16, v124
	v_and_b32_e32 v123, 0xffff0000, v124
	v_lshlrev_b32_e32 v124, 16, v125
	v_and_b32_e32 v125, 0xffff0000, v125
	v_pk_add_f32 v[122:123], v[228:229], v[122:123]
	v_pk_add_f32 v[124:125], v[230:231], v[124:125]
	v_pk_fma_f32 v[232:233], v[122:123], v[122:123], v[232:233]
	v_pk_fma_f32 v[232:233], v[124:125], v[124:125], v[232:233]
	global_load_dwordx2 v[186:187], v241, s[32:33] offset:3072
	global_load_dwordx2 v[188:189], v241, s[34:35] offset:3072
	s_waitcnt vmcnt(30)
	v_lshlrev_b32_e32 v228, 16, v126
	v_and_b32_e32 v229, 0xffff0000, v126
	v_lshlrev_b32_e32 v230, 16, v127
	v_and_b32_e32 v231, 0xffff0000, v127
	v_lshlrev_b32_e32 v126, 16, v128
	v_and_b32_e32 v127, 0xffff0000, v128
	v_lshlrev_b32_e32 v128, 16, v129
	v_and_b32_e32 v129, 0xffff0000, v129
	v_pk_add_f32 v[126:127], v[228:229], v[126:127]
	v_pk_add_f32 v[128:129], v[230:231], v[128:129]
	v_pk_fma_f32 v[232:233], v[126:127], v[126:127], v[232:233]
	v_pk_fma_f32 v[232:233], v[128:129], v[128:129], v[232:233]
	global_load_dwordx2 v[190:191], v241, s[32:33] offset:3584
	global_load_dwordx2 v[192:193], v241, s[34:35] offset:3584
	v_add_f32_e32 v217, v232, v233
	s_nop 1
	v_add_f32_dpp v217, v217, v217 row_shr:1 row_mask:0xf bank_mask:0xf bound_ctrl:1
	s_nop 1
	v_add_f32_dpp v217, v217, v217 row_shr:2 row_mask:0xf bank_mask:0xf bound_ctrl:1
	s_nop 1
	v_add_f32_dpp v217, v217, v217 row_shr:4 row_mask:0xf bank_mask:0xf bound_ctrl:1
	s_nop 1
	v_add_f32_dpp v217, v217, v217 row_shr:8 row_mask:0xf bank_mask:0xf bound_ctrl:1
	v_mov_b32_e32 v222, v195
	s_nop 1
	v_mov_b32_dpp v222, v217 row_bcast:15 row_mask:0xa bank_mask:0xf bound_ctrl:1
	v_add_f32_e32 v217, v217, v222
	v_mov_b32_e32 v222, v195
	s_nop 1
	v_mov_b32_dpp v222, v217 row_bcast:31 row_mask:0xc bank_mask:0xf bound_ctrl:1
	v_add_f32_e32 v217, v217, v222
	s_nop 1
	v_readlane_b32 s0, v217, 63
	s_nop 3
	v_fma_f32 v217, s0, v209, v202
	v_cmp_gt_f32_e32 vcc, s25, v217
	v_mul_f32_e32 v222, 0x4f800000, v217
	s_nop 1
	v_cndmask_b32_e32 v217, v217, v222, vcc
	v_sqrt_f32_e32 v222, v217
	s_nop 1
	v_add_u32_e32 v223, -1, v222
	v_fma_f32 v226, -v223, v222, v217
	v_cmp_ge_f32_e64 s[68:69], 0, v226
	v_add_u32_e32 v226, 1, v222
	s_nop 1
	v_cndmask_b32_e64 v223, v222, v223, s[68:69]
	v_fma_f32 v222, -v226, v222, v217
	v_cmp_lt_f32_e64 s[68:69], 0, v222
	s_nop 1
	v_cndmask_b32_e64 v222, v223, v226, s[68:69]
	v_mul_f32_e32 v223, 0x37800000, v222
	v_cndmask_b32_e32 v222, v222, v223, vcc
	v_cmp_class_f32_e32 vcc, v217, v203
	s_nop 1
	v_cndmask_b32_e32 v217, v222, v217, vcc
	v_div_scale_f32 v222, s[68:69], v217, v217, 1.0
	v_rcp_f32_e32 v223, v222
	s_nop 1
	v_fma_f32 v226, -v222, v223, 1.0
	v_fmac_f32_e32 v223, v226, v223
	v_div_scale_f32 v226, vcc, 1.0, v217, 1.0
	v_mul_f32_e32 v227, v226, v223
	v_fma_f32 v194, -v222, v227, v226
	v_fmac_f32_e32 v227, v194, v223
	v_fma_f32 v222, -v222, v227, v226
	s_nop 1
	v_div_fmas_f32 v222, v222, v223, v227
	v_div_fixup_f32 v234, v222, v217, 1.0
	v_pk_mul_f32 v[66:67], v[66:67], v[234:235] op_sel_hi:[1,0]
	v_pk_mul_f32 v[68:69], v[68:69], v[234:235] op_sel_hi:[1,0]
	v_pk_mul_f32 v[66:67], v[2:3], v[66:67]
	v_pk_mul_f32 v[68:69], v[4:5], v[68:69]
	global_store_dwordx4 v236, v[66:69], s[36:37]
	v_pk_mul_f32 v[70:71], v[70:71], v[234:235] op_sel_hi:[1,0]
	v_pk_mul_f32 v[72:73], v[72:73], v[234:235] op_sel_hi:[1,0]
	v_pk_mul_f32 v[70:71], v[6:7], v[70:71]
	v_pk_mul_f32 v[72:73], v[8:9], v[72:73]
	global_store_dwordx4 v236, v[70:73], s[36:37] offset:1024
	v_pk_mul_f32 v[74:75], v[74:75], v[234:235] op_sel_hi:[1,0]
	v_pk_mul_f32 v[76:77], v[76:77], v[234:235] op_sel_hi:[1,0]
	v_pk_mul_f32 v[74:75], v[10:11], v[74:75]
	v_pk_mul_f32 v[76:77], v[12:13], v[76:77]
	global_store_dwordx4 v236, v[74:77], s[36:37] offset:2048
	v_pk_mul_f32 v[78:79], v[78:79], v[234:235] op_sel_hi:[1,0]
	v_pk_mul_f32 v[80:81], v[80:81], v[234:235] op_sel_hi:[1,0]
	v_pk_mul_f32 v[78:79], v[14:15], v[78:79]
	v_pk_mul_f32 v[80:81], v[16:17], v[80:81]
	global_store_dwordx4 v236, v[78:81], s[36:37] offset:3072
	v_pk_mul_f32 v[82:83], v[82:83], v[234:235] op_sel_hi:[1,0]
	v_pk_mul_f32 v[84:85], v[84:85], v[234:235] op_sel_hi:[1,0]
	v_pk_mul_f32 v[82:83], v[18:19], v[82:83]
	v_pk_mul_f32 v[84:85], v[20:21], v[84:85]
	global_store_dwordx4 v237, v[82:85], s[36:37]
	v_pk_mul_f32 v[86:87], v[86:87], v[234:235] op_sel_hi:[1,0]
	v_pk_mul_f32 v[88:89], v[88:89], v[234:235] op_sel_hi:[1,0]
	v_pk_mul_f32 v[86:87], v[22:23], v[86:87]
	v_pk_mul_f32 v[88:89], v[24:25], v[88:89]
	global_store_dwordx4 v237, v[86:89], s[36:37] offset:1024
	v_pk_mul_f32 v[90:91], v[90:91], v[234:235] op_sel_hi:[1,0]
	v_pk_mul_f32 v[92:93], v[92:93], v[234:235] op_sel_hi:[1,0]
	v_pk_mul_f32 v[90:91], v[26:27], v[90:91]
	v_pk_mul_f32 v[92:93], v[28:29], v[92:93]
	global_store_dwordx4 v237, v[90:93], s[36:37] offset:2048
	v_pk_mul_f32 v[94:95], v[94:95], v[234:235] op_sel_hi:[1,0]
	v_pk_mul_f32 v[96:97], v[96:97], v[234:235] op_sel_hi:[1,0]
	v_pk_mul_f32 v[94:95], v[30:31], v[94:95]
	v_pk_mul_f32 v[96:97], v[32:33], v[96:97]
	global_store_dwordx4 v237, v[94:97], s[36:37] offset:3072
	v_pk_mul_f32 v[98:99], v[98:99], v[234:235] op_sel_hi:[1,0]
	v_pk_mul_f32 v[100:101], v[100:101], v[234:235] op_sel_hi:[1,0]
	v_pk_mul_f32 v[98:99], v[34:35], v[98:99]
	v_pk_mul_f32 v[100:101], v[36:37], v[100:101]
	global_store_dwordx4 v238, v[98:101], s[36:37]
	v_pk_mul_f32 v[102:103], v[102:103], v[234:235] op_sel_hi:[1,0]
	v_pk_mul_f32 v[104:105], v[104:105], v[234:235] op_sel_hi:[1,0]
	v_pk_mul_f32 v[102:103], v[38:39], v[102:103]
	v_pk_mul_f32 v[104:105], v[40:41], v[104:105]
	global_store_dwordx4 v238, v[102:105], s[36:37] offset:1024
	v_pk_mul_f32 v[106:107], v[106:107], v[234:235] op_sel_hi:[1,0]
	v_pk_mul_f32 v[108:109], v[108:109], v[234:235] op_sel_hi:[1,0]
	v_pk_mul_f32 v[106:107], v[42:43], v[106:107]
	v_pk_mul_f32 v[108:109], v[44:45], v[108:109]
	global_store_dwordx4 v238, v[106:109], s[36:37] offset:2048
	v_pk_mul_f32 v[110:111], v[110:111], v[234:235] op_sel_hi:[1,0]
	v_pk_mul_f32 v[112:113], v[112:113], v[234:235] op_sel_hi:[1,0]
	v_pk_mul_f32 v[110:111], v[46:47], v[110:111]
	v_pk_mul_f32 v[112:113], v[48:49], v[112:113]
	global_store_dwordx4 v238, v[110:113], s[36:37] offset:3072
	v_pk_mul_f32 v[114:115], v[114:115], v[234:235] op_sel_hi:[1,0]
	v_pk_mul_f32 v[116:117], v[116:117], v[234:235] op_sel_hi:[1,0]
	v_pk_mul_f32 v[114:115], v[50:51], v[114:115]
	v_pk_mul_f32 v[116:117], v[52:53], v[116:117]
	global_store_dwordx4 v239, v[114:117], s[36:37]
	v_pk_mul_f32 v[118:119], v[118:119], v[234:235] op_sel_hi:[1,0]
	v_pk_mul_f32 v[120:121], v[120:121], v[234:235] op_sel_hi:[1,0]
	v_pk_mul_f32 v[118:119], v[54:55], v[118:119]
	v_pk_mul_f32 v[120:121], v[56:57], v[120:121]
	global_store_dwordx4 v239, v[118:121], s[36:37] offset:1024
	v_pk_mul_f32 v[122:123], v[122:123], v[234:235] op_sel_hi:[1,0]
	v_pk_mul_f32 v[124:125], v[124:125], v[234:235] op_sel_hi:[1,0]
	v_pk_mul_f32 v[122:123], v[58:59], v[122:123]
	v_pk_mul_f32 v[124:125], v[60:61], v[124:125]
	global_store_dwordx4 v239, v[122:125], s[36:37] offset:2048
	v_pk_mul_f32 v[126:127], v[126:127], v[234:235] op_sel_hi:[1,0]
	v_pk_mul_f32 v[128:129], v[128:129], v[234:235] op_sel_hi:[1,0]
	v_pk_mul_f32 v[126:127], v[62:63], v[126:127]
	v_pk_mul_f32 v[128:129], v[64:65], v[128:129]
	global_store_dwordx4 v239, v[126:129], s[36:37] offset:3072
	s_cmp_eq_u32 s39, 1
	s_cbranch_scc1 .Lph_done
.Lph_loop:
	s_mov_b32 s40, s38
	s_add_i32 s38, s40, s96
	s_cmpk_gt_i32 s38, 0x3fff
	s_cselect_b32 s39, 1, 0
	s_cselect_b32 s38, s40, s38
	s_lshl_b32 s41, s38, 13
	s_add_u32 s32, s8, s41
	s_addc_u32 s33, s9, 0
	s_add_u32 s34, s10, s41
	s_addc_u32 s35, s11, 0
	s_lshl_b32 s41, s40, 14
	s_add_u32 s36, s4, s41
	s_addc_u32 s37, s5, 0
	s_waitcnt vmcnt(46)
	v_lshlrev_b32_e32 v228, 16, v130
	v_and_b32_e32 v229, 0xffff0000, v130
	v_lshlrev_b32_e32 v230, 16, v131
	v_and_b32_e32 v231, 0xffff0000, v131
	v_lshlrev_b32_e32 v130, 16, v132
	v_and_b32_e32 v131, 0xffff0000, v132
	v_lshlrev_b32_e32 v132, 16, v133
	v_and_b32_e32 v133, 0xffff0000, v133
	v_pk_add_f32 v[130:131], v[228:229], v[130:131]
	v_pk_add_f32 v[132:133], v[230:231], v[132:133]
	v_pk_mul_f32 v[232:233], v[130:131], v[130:131]
	v_pk_fma_f32 v[232:233], v[132:133], v[132:133], v[232:233]
	global_load_dwordx2 v[66:67], v240, s[32:33]
	global_load_dwordx2 v[68:69], v240, s[34:35]
	s_waitcnt vmcnt(46)
	v_lshlrev_b32_e32 v228, 16, v134
	v_and_b32_e32 v229, 0xffff0000, v134
	v_lshlrev_b32_e32 v230, 16, v135
	v_and_b32_e32 v231, 0xffff0000, v135
	v_lshlrev_b32_e32 v134, 16, v136
	v_and_b32_e32 v135, 0xffff0000, v136
	v_lshlrev_b32_e32 v136, 16, v137
	v_and_b32_e32 v137, 0xffff0000, v137
	v_pk_add_f32 v[134:135], v[228:229], v[134:135]
	v_pk_add_f32 v[136:137], v[230:231], v[136:137]
	v_pk_fma_f32 v[232:233], v[134:135], v[134:135], v[232:233]
	v_pk_fma_f32 v[232:233], v[136:137], v[136:137], v[232:233]
	global_load_dwordx2 v[70:71], v240, s[32:33] offset:512
	global_load_dwordx2 v[72:73], v240, s[34:35] offset:512
	s_waitcnt vmcnt(46)
	v_lshlrev_b32_e32 v228, 16, v138
	v_and_b32_e32 v229, 0xffff0000, v138
	v_lshlrev_b32_e32 v230, 16, v139
	v_and_b32_e32 v231, 0xffff0000, v139
	v_lshlrev_b32_e32 v138, 16, v140
	v_and_b32_e32 v139, 0xffff0000, v140
	v_lshlrev_b32_e32 v140, 16, v141
	v_and_b32_e32 v141, 0xffff0000, v141
	v_pk_add_f32 v[138:139], v[228:229], v[138:139]
	v_pk_add_f32 v[140:141], v[230:231], v[140:141]
	v_pk_fma_f32 v[232:233], v[138:139], v[138:139], v[232:233]
	v_pk_fma_f32 v[232:233], v[140:141], v[140:141], v[232:233]
	global_load_dwordx2 v[74:75], v240, s[32:33] offset:1024
	global_load_dwordx2 v[76:77], v240, s[34:35] offset:1024
	s_waitcnt vmcnt(46)
	v_lshlrev_b32_e32 v228, 16, v142
	v_and_b32_e32 v229, 0xffff0000, v142
	v_lshlrev_b32_e32 v230, 16, v143
	v_and_b32_e32 v231, 0xffff0000, v143
	v_lshlrev_b32_e32 v142, 16, v144
	v_and_b32_e32 v143, 0xffff0000, v144
	v_lshlrev_b32_e32 v144, 16, v145
	v_and_b32_e32 v145, 0xffff0000, v145
	v_pk_add_f32 v[142:143], v[228:229], v[142:143]
	v_pk_add_f32 v[144:145], v[230:231], v[144:145]
	v_pk_fma_f32 v[232:233], v[142:143], v[142:143], v[232:233]
	v_pk_fma_f32 v[232:233], v[144:145], v[144:145], v[232:233]
	global_load_dwordx2 v[78:79], v240, s[32:33] offset:1536
	global_load_dwordx2 v[80:81], v240, s[34:35] offset:1536
	s_waitcnt vmcnt(46)
	v_lshlrev_b32_e32 v228, 16, v146
	v_and_b32_e32 v229, 0xffff0000, v146
	v_lshlrev_b32_e32 v230, 16, v147
	v_and_b32_e32 v231, 0xffff0000, v147
	v_lshlrev_b32_e32 v146, 16, v148
	v_and_b32_e32 v147, 0xffff0000, v148
	v_lshlrev_b32_e32 v148, 16, v149
	v_and_b32_e32 v149, 0xffff0000, v149
	v_pk_add_f32 v[146:147], v[228:229], v[146:147]
	v_pk_add_f32 v[148:149], v[230:231], v[148:149]
	v_pk_fma_f32 v[232:233], v[146:147], v[146:147], v[232:233]
	v_pk_fma_f32 v[232:233], v[148:149], v[148:149], v[232:233]
	global_load_dwordx2 v[82:83], v240, s[32:33] offset:2048
	global_load_dwordx2 v[84:85], v240, s[34:35] offset:2048
	s_waitcnt vmcnt(46)
	v_lshlrev_b32_e32 v228, 16, v150
	v_and_b32_e32 v229, 0xffff0000, v150
	v_lshlrev_b32_e32 v230, 16, v151
	v_and_b32_e32 v231, 0xffff0000, v151
	v_lshlrev_b32_e32 v150, 16, v152
	v_and_b32_e32 v151, 0xffff0000, v152
	v_lshlrev_b32_e32 v152, 16, v153
	v_and_b32_e32 v153, 0xffff0000, v153
	v_pk_add_f32 v[150:151], v[228:229], v[150:151]
	v_pk_add_f32 v[152:153], v[230:231], v[152:153]
	v_pk_fma_f32 v[232:233], v[150:151], v[150:151], v[232:233]
	v_pk_fma_f32 v[232:233], v[152:153], v[152:153], v[232:233]
	global_load_dwordx2 v[86:87], v240, s[32:33] offset:2560
	global_load_dwordx2 v[88:89], v240, s[34:35] offset:2560
	s_waitcnt vmcnt(46)
	v_lshlrev_b32_e32 v228, 16, v154
	v_and_b32_e32 v229, 0xffff0000, v154
	v_lshlrev_b32_e32 v230, 16, v155
	v_and_b32_e32 v231, 0xffff0000, v155
	v_lshlrev_b32_e32 v154, 16, v156
	v_and_b32_e32 v155, 0xffff0000, v156
	v_lshlrev_b32_e32 v156, 16, v157
	v_and_b32_e32 v157, 0xffff0000, v157
	v_pk_add_f32 v[154:155], v[228:229], v[154:155]
	v_pk_add_f32 v[156:157], v[230:231], v[156:157]
	v_pk_fma_f32 v[232:233], v[154:155], v[154:155], v[232:233]
	v_pk_fma_f32 v[232:233], v[156:157], v[156:157], v[232:233]
	global_load_dwordx2 v[90:91], v240, s[32:33] offset:3072
	global_load_dwordx2 v[92:93], v240, s[34:35] offset:3072
	s_waitcnt vmcnt(46)
	v_lshlrev_b32_e32 v228, 16, v158
	v_and_b32_e32 v229, 0xffff0000, v158
	v_lshlrev_b32_e32 v230, 16, v159
	v_and_b32_e32 v231, 0xffff0000, v159
	v_lshlrev_b32_e32 v158, 16, v160
	v_and_b32_e32 v159, 0xffff0000, v160
	v_lshlrev_b32_e32 v160, 16, v161
	v_and_b32_e32 v161, 0xffff0000, v161
	v_pk_add_f32 v[158:159], v[228:229], v[158:159]
	v_pk_add_f32 v[160:161], v[230:231], v[160:161]
	v_pk_fma_f32 v[232:233], v[158:159], v[158:159], v[232:233]
	v_pk_fma_f32 v[232:233], v[160:161], v[160:161], v[232:233]
	global_load_dwordx2 v[94:95], v240, s[32:33] offset:3584
	global_load_dwordx2 v[96:97], v240, s[34:35] offset:3584
	s_waitcnt vmcnt(46)
	v_lshlrev_b32_e32 v228, 16, v162
	v_and_b32_e32 v229, 0xffff0000, v162
	v_lshlrev_b32_e32 v230, 16, v163
	v_and_b32_e32 v231, 0xffff0000, v163
	v_lshlrev_b32_e32 v162, 16, v164
	v_and_b32_e32 v163, 0xffff0000, v164
	v_lshlrev_b32_e32 v164, 16, v165
	v_and_b32_e32 v165, 0xffff0000, v165
	v_pk_add_f32 v[162:163], v[228:229], v[162:163]
	v_pk_add_f32 v[164:165], v[230:231], v[164:165]
	v_pk_fma_f32 v[232:233], v[162:163], v[162:163], v[232:233]
	v_pk_fma_f32 v[232:233], v[164:165], v[164:165], v[232:233]
	global_load_dwordx2 v[98:99], v241, s[32:33]
	global_load_dwordx2 v[100:101], v241, s[34:35]
	s_waitcnt vmcnt(46)
	v_lshlrev_b32_e32 v228, 16, v166
	v_and_b32_e32 v229, 0xffff0000, v166
	v_lshlrev_b32_e32 v230, 16, v167
	v_and_b32_e32 v231, 0xffff0000, v167
	v_lshlrev_b32_e32 v166, 16, v168
	v_and_b32_e32 v167, 0xffff0000, v168
	v_lshlrev_b32_e32 v168, 16, v169
	v_and_b32_e32 v169, 0xffff0000, v169
	v_pk_add_f32 v[166:167], v[228:229], v[166:167]
	v_pk_add_f32 v[168:169], v[230:231], v[168:169]
	v_pk_fma_f32 v[232:233], v[166:167], v[166:167], v[232:233]
	v_pk_fma_f32 v[232:233], v[168:169], v[168:169], v[232:233]
	global_load_dwordx2 v[102:103], v241, s[32:33] offset:512
	global_load_dwordx2 v[104:105], v241, s[34:35] offset:512
	s_waitcnt vmcnt(46)
	v_lshlrev_b32_e32 v228, 16, v170
	v_and_b32_e32 v229, 0xffff0000, v170
	v_lshlrev_b32_e32 v230, 16, v171
	v_and_b32_e32 v231, 0xffff0000, v171
	v_lshlrev_b32_e32 v170, 16, v172
	v_and_b32_e32 v171, 0xffff0000, v172
	v_lshlrev_b32_e32 v172, 16, v173
	v_and_b32_e32 v173, 0xffff0000, v173
	v_pk_add_f32 v[170:171], v[228:229], v[170:171]
	v_pk_add_f32 v[172:173], v[230:231], v[172:173]
	v_pk_fma_f32 v[232:233], v[170:171], v[170:171], v[232:233]
	v_pk_fma_f32 v[232:233], v[172:173], v[172:173], v[232:233]
	global_load_dwordx2 v[106:107], v241, s[32:33] offset:1024
	global_load_dwordx2 v[108:109], v241, s[34:35] offset:1024
	s_waitcnt vmcnt(46)
	v_lshlrev_b32_e32 v228, 16, v174
	v_and_b32_e32 v229, 0xffff0000, v174
	v_lshlrev_b32_e32 v230, 16, v175
	v_and_b32_e32 v231, 0xffff0000, v175
	v_lshlrev_b32_e32 v174, 16, v176
	v_and_b32_e32 v175, 0xffff0000, v176
	v_lshlrev_b32_e32 v176, 16, v177
	v_and_b32_e32 v177, 0xffff0000, v177
	v_pk_add_f32 v[174:175], v[228:229], v[174:175]
	v_pk_add_f32 v[176:177], v[230:231], v[176:177]
	v_pk_fma_f32 v[232:233], v[174:175], v[174:175], v[232:233]
	v_pk_fma_f32 v[232:233], v[176:177], v[176:177], v[232:233]
	global_load_dwordx2 v[110:111], v241, s[32:33] offset:1536
	global_load_dwordx2 v[112:113], v241, s[34:35] offset:1536
	s_waitcnt vmcnt(46)
	v_lshlrev_b32_e32 v228, 16, v178
	v_and_b32_e32 v229, 0xffff0000, v178
	v_lshlrev_b32_e32 v230, 16, v179
	v_and_b32_e32 v231, 0xffff0000, v179
	v_lshlrev_b32_e32 v178, 16, v180
	v_and_b32_e32 v179, 0xffff0000, v180
	v_lshlrev_b32_e32 v180, 16, v181
	v_and_b32_e32 v181, 0xffff0000, v181
	v_pk_add_f32 v[178:179], v[228:229], v[178:179]
	v_pk_add_f32 v[180:181], v[230:231], v[180:181]
	v_pk_fma_f32 v[232:233], v[178:179], v[178:179], v[232:233]
	v_pk_fma_f32 v[232:233], v[180:181], v[180:181], v[232:233]
	global_load_dwordx2 v[114:115], v241, s[32:33] offset:2048
	global_load_dwordx2 v[116:117], v241, s[34:35] offset:2048
	s_waitcnt vmcnt(46)
	v_lshlrev_b32_e32 v228, 16, v182
	v_and_b32_e32 v229, 0xffff0000, v182
	v_lshlrev_b32_e32 v230, 16, v183
	v_and_b32_e32 v231, 0xffff0000, v183
	v_lshlrev_b32_e32 v182, 16, v184
	v_and_b32_e32 v183, 0xffff0000, v184
	v_lshlrev_b32_e32 v184, 16, v185
	v_and_b32_e32 v185, 0xffff0000, v185
	v_pk_add_f32 v[182:183], v[228:229], v[182:183]
	v_pk_add_f32 v[184:185], v[230:231], v[184:185]
	v_pk_fma_f32 v[232:233], v[182:183], v[182:183], v[232:233]
	v_pk_fma_f32 v[232:233], v[184:185], v[184:185], v[232:233]
	global_load_dwordx2 v[118:119], v241, s[32:33] offset:2560
	global_load_dwordx2 v[120:121], v241, s[34:35] offset:2560
	s_waitcnt vmcnt(46)
	v_lshlrev_b32_e32 v228, 16, v186
	v_and_b32_e32 v229, 0xffff0000, v186
	v_lshlrev_b32_e32 v230, 16, v187
	v_and_b32_e32 v231, 0xffff0000, v187
	v_lshlrev_b32_e32 v186, 16, v188
	v_and_b32_e32 v187, 0xffff0000, v188
	v_lshlrev_b32_e32 v188, 16, v189
	v_and_b32_e32 v189, 0xffff0000, v189
	v_pk_add_f32 v[186:187], v[228:229], v[186:187]
	v_pk_add_f32 v[188:189], v[230:231], v[188:189]
	v_pk_fma_f32 v[232:233], v[186:187], v[186:187], v[232:233]
	v_pk_fma_f32 v[232:233], v[188:189], v[188:189], v[232:233]
	global_load_dwordx2 v[122:123], v241, s[32:33] offset:3072
	global_load_dwordx2 v[124:125], v241, s[34:35] offset:3072
	s_waitcnt vmcnt(46)
	v_lshlrev_b32_e32 v228, 16, v190
	v_and_b32_e32 v229, 0xffff0000, v190
	v_lshlrev_b32_e32 v230, 16, v191
	v_and_b32_e32 v231, 0xffff0000, v191
	v_lshlrev_b32_e32 v190, 16, v192
	v_and_b32_e32 v191, 0xffff0000, v192
	v_lshlrev_b32_e32 v192, 16, v193
	v_and_b32_e32 v193, 0xffff0000, v193
	v_pk_add_f32 v[190:191], v[228:229], v[190:191]
	v_pk_add_f32 v[192:193], v[230:231], v[192:193]
	v_pk_fma_f32 v[232:233], v[190:191], v[190:191], v[232:233]
	v_pk_fma_f32 v[232:233], v[192:193], v[192:193], v[232:233]
	global_load_dwordx2 v[126:127], v241, s[32:33] offset:3584
	global_load_dwordx2 v[128:129], v241, s[34:35] offset:3584
	v_add_f32_e32 v217, v232, v233
	s_nop 1
	v_add_f32_dpp v217, v217, v217 row_shr:1 row_mask:0xf bank_mask:0xf bound_ctrl:1
	s_nop 1
	v_add_f32_dpp v217, v217, v217 row_shr:2 row_mask:0xf bank_mask:0xf bound_ctrl:1
	s_nop 1
	v_add_f32_dpp v217, v217, v217 row_shr:4 row_mask:0xf bank_mask:0xf bound_ctrl:1
	s_nop 1
	v_add_f32_dpp v217, v217, v217 row_shr:8 row_mask:0xf bank_mask:0xf bound_ctrl:1
	v_mov_b32_e32 v222, v195
	s_nop 1
	v_mov_b32_dpp v222, v217 row_bcast:15 row_mask:0xa bank_mask:0xf bound_ctrl:1
	v_add_f32_e32 v217, v217, v222
	v_mov_b32_e32 v222, v195
	s_nop 1
	v_mov_b32_dpp v222, v217 row_bcast:31 row_mask:0xc bank_mask:0xf bound_ctrl:1
	v_add_f32_e32 v217, v217, v222
	s_nop 1
	v_readlane_b32 s0, v217, 63
	s_nop 3
	v_fma_f32 v217, s0, v209, v202
	v_cmp_gt_f32_e32 vcc, s25, v217
	v_mul_f32_e32 v222, 0x4f800000, v217
	s_nop 1
	v_cndmask_b32_e32 v217, v217, v222, vcc
	v_sqrt_f32_e32 v222, v217
	s_nop 1
	v_add_u32_e32 v223, -1, v222
	v_fma_f32 v226, -v223, v222, v217
	v_cmp_ge_f32_e64 s[68:69], 0, v226
	v_add_u32_e32 v226, 1, v222
	s_nop 1
	v_cndmask_b32_e64 v223, v222, v223, s[68:69]
	v_fma_f32 v222, -v226, v222, v217
	v_cmp_lt_f32_e64 s[68:69], 0, v222
	s_nop 1
	v_cndmask_b32_e64 v222, v223, v226, s[68:69]
	v_mul_f32_e32 v223, 0x37800000, v222
	v_cndmask_b32_e32 v222, v222, v223, vcc
	v_cmp_class_f32_e32 vcc, v217, v203
	s_nop 1
	v_cndmask_b32_e32 v217, v222, v217, vcc
	v_div_scale_f32 v222, s[68:69], v217, v217, 1.0
	v_rcp_f32_e32 v223, v222
	s_nop 1
	v_fma_f32 v226, -v222, v223, 1.0
	v_fmac_f32_e32 v223, v226, v223
	v_div_scale_f32 v226, vcc, 1.0, v217, 1.0
	v_mul_f32_e32 v227, v226, v223
	v_fma_f32 v194, -v222, v227, v226
	v_fmac_f32_e32 v227, v194, v223
	v_fma_f32 v222, -v222, v227, v226
	s_nop 1
	v_div_fmas_f32 v222, v222, v223, v227
	v_div_fixup_f32 v234, v222, v217, 1.0
	s_waitcnt vmcnt(32)
	v_pk_mul_f32 v[130:131], v[130:131], v[234:235] op_sel_hi:[1,0]
	v_pk_mul_f32 v[132:133], v[132:133], v[234:235] op_sel_hi:[1,0]
	v_pk_mul_f32 v[130:131], v[2:3], v[130:131]
	v_pk_mul_f32 v[132:133], v[4:5], v[132:133]
	global_store_dwordx4 v236, v[130:133], s[36:37]
	v_pk_mul_f32 v[134:135], v[134:135], v[234:235] op_sel_hi:[1,0]
	v_pk_mul_f32 v[136:137], v[136:137], v[234:235] op_sel_hi:[1,0]
	v_pk_mul_f32 v[134:135], v[6:7], v[134:135]
	v_pk_mul_f32 v[136:137], v[8:9], v[136:137]
	global_store_dwordx4 v236, v[134:137], s[36:37] offset:1024
	v_pk_mul_f32 v[138:139], v[138:139], v[234:235] op_sel_hi:[1,0]
	v_pk_mul_f32 v[140:141], v[140:141], v[234:235] op_sel_hi:[1,0]
	v_pk_mul_f32 v[138:139], v[10:11], v[138:139]
	v_pk_mul_f32 v[140:141], v[12:13], v[140:141]
	global_store_dwordx4 v236, v[138:141], s[36:37] offset:2048
	v_pk_mul_f32 v[142:143], v[142:143], v[234:235] op_sel_hi:[1,0]
	v_pk_mul_f32 v[144:145], v[144:145], v[234:235] op_sel_hi:[1,0]
	v_pk_mul_f32 v[142:143], v[14:15], v[142:143]
	v_pk_mul_f32 v[144:145], v[16:17], v[144:145]
	global_store_dwordx4 v236, v[142:145], s[36:37] offset:3072
	v_pk_mul_f32 v[146:147], v[146:147], v[234:235] op_sel_hi:[1,0]
	v_pk_mul_f32 v[148:149], v[148:149], v[234:235] op_sel_hi:[1,0]
	v_pk_mul_f32 v[146:147], v[18:19], v[146:147]
	v_pk_mul_f32 v[148:149], v[20:21], v[148:149]
	global_store_dwordx4 v237, v[146:149], s[36:37]
	v_pk_mul_f32 v[150:151], v[150:151], v[234:235] op_sel_hi:[1,0]
	v_pk_mul_f32 v[152:153], v[152:153], v[234:235] op_sel_hi:[1,0]
	v_pk_mul_f32 v[150:151], v[22:23], v[150:151]
	v_pk_mul_f32 v[152:153], v[24:25], v[152:153]
	global_store_dwordx4 v237, v[150:153], s[36:37] offset:1024
	v_pk_mul_f32 v[154:155], v[154:155], v[234:235] op_sel_hi:[1,0]
	v_pk_mul_f32 v[156:157], v[156:157], v[234:235] op_sel_hi:[1,0]
	v_pk_mul_f32 v[154:155], v[26:27], v[154:155]
	v_pk_mul_f32 v[156:157], v[28:29], v[156:157]
	global_store_dwordx4 v237, v[154:157], s[36:37] offset:2048
	v_pk_mul_f32 v[158:159], v[158:159], v[234:235] op_sel_hi:[1,0]
	v_pk_mul_f32 v[160:161], v[160:161], v[234:235] op_sel_hi:[1,0]
	v_pk_mul_f32 v[158:159], v[30:31], v[158:159]
	v_pk_mul_f32 v[160:161], v[32:33], v[160:161]
	global_store_dwordx4 v237, v[158:161], s[36:37] offset:3072
	v_pk_mul_f32 v[162:163], v[162:163], v[234:235] op_sel_hi:[1,0]
	v_pk_mul_f32 v[164:165], v[164:165], v[234:235] op_sel_hi:[1,0]
	v_pk_mul_f32 v[162:163], v[34:35], v[162:163]
	v_pk_mul_f32 v[164:165], v[36:37], v[164:165]
	global_store_dwordx4 v238, v[162:165], s[36:37]
	v_pk_mul_f32 v[166:167], v[166:167], v[234:235] op_sel_hi:[1,0]
	v_pk_mul_f32 v[168:169], v[168:169], v[234:235] op_sel_hi:[1,0]
	v_pk_mul_f32 v[166:167], v[38:39], v[166:167]
	v_pk_mul_f32 v[168:169], v[40:41], v[168:169]
	global_store_dwordx4 v238, v[166:169], s[36:37] offset:1024
	v_pk_mul_f32 v[170:171], v[170:171], v[234:235] op_sel_hi:[1,0]
	v_pk_mul_f32 v[172:173], v[172:173], v[234:235] op_sel_hi:[1,0]
	v_pk_mul_f32 v[170:171], v[42:43], v[170:171]
	v_pk_mul_f32 v[172:173], v[44:45], v[172:173]
	global_store_dwordx4 v238, v[170:173], s[36:37] offset:2048
	v_pk_mul_f32 v[174:175], v[174:175], v[234:235] op_sel_hi:[1,0]
	v_pk_mul_f32 v[176:177], v[176:177], v[234:235] op_sel_hi:[1,0]
	v_pk_mul_f32 v[174:175], v[46:47], v[174:175]
	v_pk_mul_f32 v[176:177], v[48:49], v[176:177]
	global_store_dwordx4 v238, v[174:177], s[36:37] offset:3072
	v_pk_mul_f32 v[178:179], v[178:179], v[234:235] op_sel_hi:[1,0]
	v_pk_mul_f32 v[180:181], v[180:181], v[234:235] op_sel_hi:[1,0]
	v_pk_mul_f32 v[178:179], v[50:51], v[178:179]
	v_pk_mul_f32 v[180:181], v[52:53], v[180:181]
	global_store_dwordx4 v239, v[178:181], s[36:37]
	v_pk_mul_f32 v[182:183], v[182:183], v[234:235] op_sel_hi:[1,0]
	v_pk_mul_f32 v[184:185], v[184:185], v[234:235] op_sel_hi:[1,0]
	v_pk_mul_f32 v[182:183], v[54:55], v[182:183]
	v_pk_mul_f32 v[184:185], v[56:57], v[184:185]
	global_store_dwordx4 v239, v[182:185], s[36:37] offset:1024
	v_pk_mul_f32 v[186:187], v[186:187], v[234:235] op_sel_hi:[1,0]
	v_pk_mul_f32 v[188:189], v[188:189], v[234:235] op_sel_hi:[1,0]
	v_pk_mul_f32 v[186:187], v[58:59], v[186:187]
	v_pk_mul_f32 v[188:189], v[60:61], v[188:189]
	global_store_dwordx4 v239, v[186:189], s[36:37] offset:2048
	v_pk_mul_f32 v[190:191], v[190:191], v[234:235] op_sel_hi:[1,0]
	v_pk_mul_f32 v[192:193], v[192:193], v[234:235] op_sel_hi:[1,0]
	v_pk_mul_f32 v[190:191], v[62:63], v[190:191]
	v_pk_mul_f32 v[192:193], v[64:65], v[192:193]
	global_store_dwordx4 v239, v[190:193], s[36:37] offset:3072
	s_cmp_eq_u32 s39, 1
	s_cbranch_scc1 .Lph_done
	s_mov_b32 s40, s38
	s_add_i32 s38, s40, s96
	s_cmpk_gt_i32 s38, 0x3fff
	s_cselect_b32 s39, 1, 0
	s_cselect_b32 s38, s40, s38
	s_lshl_b32 s41, s38, 13
	s_add_u32 s32, s8, s41
	s_addc_u32 s33, s9, 0
	s_add_u32 s34, s10, s41
	s_addc_u32 s35, s11, 0
	s_lshl_b32 s41, s40, 14
	s_add_u32 s36, s4, s41
	s_addc_u32 s37, s5, 0
	s_waitcnt vmcnt(46)
	v_lshlrev_b32_e32 v228, 16, v66
	v_and_b32_e32 v229, 0xffff0000, v66
	v_lshlrev_b32_e32 v230, 16, v67
	v_and_b32_e32 v231, 0xffff0000, v67
	v_lshlrev_b32_e32 v66, 16, v68
	v_and_b32_e32 v67, 0xffff0000, v68
	v_lshlrev_b32_e32 v68, 16, v69
	v_and_b32_e32 v69, 0xffff0000, v69
	v_pk_add_f32 v[66:67], v[228:229], v[66:67]
	v_pk_add_f32 v[68:69], v[230:231], v[68:69]
	v_pk_mul_f32 v[232:233], v[66:67], v[66:67]
	v_pk_fma_f32 v[232:233], v[68:69], v[68:69], v[232:233]
	global_load_dwordx2 v[130:131], v240, s[32:33]
	global_load_dwordx2 v[132:133], v240, s[34:35]
	s_waitcnt vmcnt(46)
	v_lshlrev_b32_e32 v228, 16, v70
	v_and_b32_e32 v229, 0xffff0000, v70
	v_lshlrev_b32_e32 v230, 16, v71
	v_and_b32_e32 v231, 0xffff0000, v71
	v_lshlrev_b32_e32 v70, 16, v72
	v_and_b32_e32 v71, 0xffff0000, v72
	v_lshlrev_b32_e32 v72, 16, v73
	v_and_b32_e32 v73, 0xffff0000, v73
	v_pk_add_f32 v[70:71], v[228:229], v[70:71]
	v_pk_add_f32 v[72:73], v[230:231], v[72:73]
	v_pk_fma_f32 v[232:233], v[70:71], v[70:71], v[232:233]
	v_pk_fma_f32 v[232:233], v[72:73], v[72:73], v[232:233]
	global_load_dwordx2 v[134:135], v240, s[32:33] offset:512
	global_load_dwordx2 v[136:137], v240, s[34:35] offset:512
	s_waitcnt vmcnt(46)
	v_lshlrev_b32_e32 v228, 16, v74
	v_and_b32_e32 v229, 0xffff0000, v74
	v_lshlrev_b32_e32 v230, 16, v75
	v_and_b32_e32 v231, 0xffff0000, v75
	v_lshlrev_b32_e32 v74, 16, v76
	v_and_b32_e32 v75, 0xffff0000, v76
	v_lshlrev_b32_e32 v76, 16, v77
	v_and_b32_e32 v77, 0xffff0000, v77
	v_pk_add_f32 v[74:75], v[228:229], v[74:75]
	v_pk_add_f32 v[76:77], v[230:231], v[76:77]
	v_pk_fma_f32 v[232:233], v[74:75], v[74:75], v[232:233]
	v_pk_fma_f32 v[232:233], v[76:77], v[76:77], v[232:233]
	global_load_dwordx2 v[138:139], v240, s[32:33] offset:1024
	global_load_dwordx2 v[140:141], v240, s[34:35] offset:1024
	s_waitcnt vmcnt(46)
	v_lshlrev_b32_e32 v228, 16, v78
	v_and_b32_e32 v229, 0xffff0000, v78
	v_lshlrev_b32_e32 v230, 16, v79
	v_and_b32_e32 v231, 0xffff0000, v79
	v_lshlrev_b32_e32 v78, 16, v80
	v_and_b32_e32 v79, 0xffff0000, v80
	v_lshlrev_b32_e32 v80, 16, v81
	v_and_b32_e32 v81, 0xffff0000, v81
	v_pk_add_f32 v[78:79], v[228:229], v[78:79]
	v_pk_add_f32 v[80:81], v[230:231], v[80:81]
	v_pk_fma_f32 v[232:233], v[78:79], v[78:79], v[232:233]
	v_pk_fma_f32 v[232:233], v[80:81], v[80:81], v[232:233]
	global_load_dwordx2 v[142:143], v240, s[32:33] offset:1536
	global_load_dwordx2 v[144:145], v240, s[34:35] offset:1536
	s_waitcnt vmcnt(46)
	v_lshlrev_b32_e32 v228, 16, v82
	v_and_b32_e32 v229, 0xffff0000, v82
	v_lshlrev_b32_e32 v230, 16, v83
	v_and_b32_e32 v231, 0xffff0000, v83
	v_lshlrev_b32_e32 v82, 16, v84
	v_and_b32_e32 v83, 0xffff0000, v84
	v_lshlrev_b32_e32 v84, 16, v85
	v_and_b32_e32 v85, 0xffff0000, v85
	v_pk_add_f32 v[82:83], v[228:229], v[82:83]
	v_pk_add_f32 v[84:85], v[230:231], v[84:85]
	v_pk_fma_f32 v[232:233], v[82:83], v[82:83], v[232:233]
	v_pk_fma_f32 v[232:233], v[84:85], v[84:85], v[232:233]
	global_load_dwordx2 v[146:147], v240, s[32:33] offset:2048
	global_load_dwordx2 v[148:149], v240, s[34:35] offset:2048
	s_waitcnt vmcnt(46)
	v_lshlrev_b32_e32 v228, 16, v86
	v_and_b32_e32 v229, 0xffff0000, v86
	v_lshlrev_b32_e32 v230, 16, v87
	v_and_b32_e32 v231, 0xffff0000, v87
	v_lshlrev_b32_e32 v86, 16, v88
	v_and_b32_e32 v87, 0xffff0000, v88
	v_lshlrev_b32_e32 v88, 16, v89
	v_and_b32_e32 v89, 0xffff0000, v89
	v_pk_add_f32 v[86:87], v[228:229], v[86:87]
	v_pk_add_f32 v[88:89], v[230:231], v[88:89]
	v_pk_fma_f32 v[232:233], v[86:87], v[86:87], v[232:233]
	v_pk_fma_f32 v[232:233], v[88:89], v[88:89], v[232:233]
	global_load_dwordx2 v[150:151], v240, s[32:33] offset:2560
	global_load_dwordx2 v[152:153], v240, s[34:35] offset:2560
	s_waitcnt vmcnt(46)
	v_lshlrev_b32_e32 v228, 16, v90
	v_and_b32_e32 v229, 0xffff0000, v90
	v_lshlrev_b32_e32 v230, 16, v91
	v_and_b32_e32 v231, 0xffff0000, v91
	v_lshlrev_b32_e32 v90, 16, v92
	v_and_b32_e32 v91, 0xffff0000, v92
	v_lshlrev_b32_e32 v92, 16, v93
	v_and_b32_e32 v93, 0xffff0000, v93
	v_pk_add_f32 v[90:91], v[228:229], v[90:91]
	v_pk_add_f32 v[92:93], v[230:231], v[92:93]
	v_pk_fma_f32 v[232:233], v[90:91], v[90:91], v[232:233]
	v_pk_fma_f32 v[232:233], v[92:93], v[92:93], v[232:233]
	global_load_dwordx2 v[154:155], v240, s[32:33] offset:3072
	global_load_dwordx2 v[156:157], v240, s[34:35] offset:3072
	s_waitcnt vmcnt(46)
	v_lshlrev_b32_e32 v228, 16, v94
	v_and_b32_e32 v229, 0xffff0000, v94
	v_lshlrev_b32_e32 v230, 16, v95
	v_and_b32_e32 v231, 0xffff0000, v95
	v_lshlrev_b32_e32 v94, 16, v96
	v_and_b32_e32 v95, 0xffff0000, v96
	v_lshlrev_b32_e32 v96, 16, v97
	v_and_b32_e32 v97, 0xffff0000, v97
	v_pk_add_f32 v[94:95], v[228:229], v[94:95]
	v_pk_add_f32 v[96:97], v[230:231], v[96:97]
	v_pk_fma_f32 v[232:233], v[94:95], v[94:95], v[232:233]
	v_pk_fma_f32 v[232:233], v[96:97], v[96:97], v[232:233]
	global_load_dwordx2 v[158:159], v240, s[32:33] offset:3584
	global_load_dwordx2 v[160:161], v240, s[34:35] offset:3584
	s_waitcnt vmcnt(46)
	v_lshlrev_b32_e32 v228, 16, v98
	v_and_b32_e32 v229, 0xffff0000, v98
	v_lshlrev_b32_e32 v230, 16, v99
	v_and_b32_e32 v231, 0xffff0000, v99
	v_lshlrev_b32_e32 v98, 16, v100
	v_and_b32_e32 v99, 0xffff0000, v100
	v_lshlrev_b32_e32 v100, 16, v101
	v_and_b32_e32 v101, 0xffff0000, v101
	v_pk_add_f32 v[98:99], v[228:229], v[98:99]
	v_pk_add_f32 v[100:101], v[230:231], v[100:101]
	v_pk_fma_f32 v[232:233], v[98:99], v[98:99], v[232:233]
	v_pk_fma_f32 v[232:233], v[100:101], v[100:101], v[232:233]
	global_load_dwordx2 v[162:163], v241, s[32:33]
	global_load_dwordx2 v[164:165], v241, s[34:35]
	s_waitcnt vmcnt(46)
	v_lshlrev_b32_e32 v228, 16, v102
	v_and_b32_e32 v229, 0xffff0000, v102
	v_lshlrev_b32_e32 v230, 16, v103
	v_and_b32_e32 v231, 0xffff0000, v103
	v_lshlrev_b32_e32 v102, 16, v104
	v_and_b32_e32 v103, 0xffff0000, v104
	v_lshlrev_b32_e32 v104, 16, v105
	v_and_b32_e32 v105, 0xffff0000, v105
	v_pk_add_f32 v[102:103], v[228:229], v[102:103]
	v_pk_add_f32 v[104:105], v[230:231], v[104:105]
	v_pk_fma_f32 v[232:233], v[102:103], v[102:103], v[232:233]
	v_pk_fma_f32 v[232:233], v[104:105], v[104:105], v[232:233]
	global_load_dwordx2 v[166:167], v241, s[32:33] offset:512
	global_load_dwordx2 v[168:169], v241, s[34:35] offset:512
	s_waitcnt vmcnt(46)
	v_lshlrev_b32_e32 v228, 16, v106
	v_and_b32_e32 v229, 0xffff0000, v106
	v_lshlrev_b32_e32 v230, 16, v107
	v_and_b32_e32 v231, 0xffff0000, v107
	v_lshlrev_b32_e32 v106, 16, v108
	v_and_b32_e32 v107, 0xffff0000, v108
	v_lshlrev_b32_e32 v108, 16, v109
	v_and_b32_e32 v109, 0xffff0000, v109
	v_pk_add_f32 v[106:107], v[228:229], v[106:107]
	v_pk_add_f32 v[108:109], v[230:231], v[108:109]
	v_pk_fma_f32 v[232:233], v[106:107], v[106:107], v[232:233]
	v_pk_fma_f32 v[232:233], v[108:109], v[108:109], v[232:233]
	global_load_dwordx2 v[170:171], v241, s[32:33] offset:1024
	global_load_dwordx2 v[172:173], v241, s[34:35] offset:1024
	s_waitcnt vmcnt(46)
	v_lshlrev_b32_e32 v228, 16, v110
	v_and_b32_e32 v229, 0xffff0000, v110
	v_lshlrev_b32_e32 v230, 16, v111
	v_and_b32_e32 v231, 0xffff0000, v111
	v_lshlrev_b32_e32 v110, 16, v112
	v_and_b32_e32 v111, 0xffff0000, v112
	v_lshlrev_b32_e32 v112, 16, v113
	v_and_b32_e32 v113, 0xffff0000, v113
	v_pk_add_f32 v[110:111], v[228:229], v[110:111]
	v_pk_add_f32 v[112:113], v[230:231], v[112:113]
	v_pk_fma_f32 v[232:233], v[110:111], v[110:111], v[232:233]
	v_pk_fma_f32 v[232:233], v[112:113], v[112:113], v[232:233]
	global_load_dwordx2 v[174:175], v241, s[32:33] offset:1536
	global_load_dwordx2 v[176:177], v241, s[34:35] offset:1536
	s_waitcnt vmcnt(46)
	v_lshlrev_b32_e32 v228, 16, v114
	v_and_b32_e32 v229, 0xffff0000, v114
	v_lshlrev_b32_e32 v230, 16, v115
	v_and_b32_e32 v231, 0xffff0000, v115
	v_lshlrev_b32_e32 v114, 16, v116
	v_and_b32_e32 v115, 0xffff0000, v116
	v_lshlrev_b32_e32 v116, 16, v117
	v_and_b32_e32 v117, 0xffff0000, v117
	v_pk_add_f32 v[114:115], v[228:229], v[114:115]
	v_pk_add_f32 v[116:117], v[230:231], v[116:117]
	v_pk_fma_f32 v[232:233], v[114:115], v[114:115], v[232:233]
	v_pk_fma_f32 v[232:233], v[116:117], v[116:117], v[232:233]
	global_load_dwordx2 v[178:179], v241, s[32:33] offset:2048
	global_load_dwordx2 v[180:181], v241, s[34:35] offset:2048
	s_waitcnt vmcnt(46)
	v_lshlrev_b32_e32 v228, 16, v118
	v_and_b32_e32 v229, 0xffff0000, v118
	v_lshlrev_b32_e32 v230, 16, v119
	v_and_b32_e32 v231, 0xffff0000, v119
	v_lshlrev_b32_e32 v118, 16, v120
	v_and_b32_e32 v119, 0xffff0000, v120
	v_lshlrev_b32_e32 v120, 16, v121
	v_and_b32_e32 v121, 0xffff0000, v121
	v_pk_add_f32 v[118:119], v[228:229], v[118:119]
	v_pk_add_f32 v[120:121], v[230:231], v[120:121]
	v_pk_fma_f32 v[232:233], v[118:119], v[118:119], v[232:233]
	v_pk_fma_f32 v[232:233], v[120:121], v[120:121], v[232:233]
	global_load_dwordx2 v[182:183], v241, s[32:33] offset:2560
	global_load_dwordx2 v[184:185], v241, s[34:35] offset:2560
	s_waitcnt vmcnt(46)
	v_lshlrev_b32_e32 v228, 16, v122
	v_and_b32_e32 v229, 0xffff0000, v122
	v_lshlrev_b32_e32 v230, 16, v123
	v_and_b32_e32 v231, 0xffff0000, v123
	v_lshlrev_b32_e32 v122, 16, v124
	v_and_b32_e32 v123, 0xffff0000, v124
	v_lshlrev_b32_e32 v124, 16, v125
	v_and_b32_e32 v125, 0xffff0000, v125
	v_pk_add_f32 v[122:123], v[228:229], v[122:123]
	v_pk_add_f32 v[124:125], v[230:231], v[124:125]
	v_pk_fma_f32 v[232:233], v[122:123], v[122:123], v[232:233]
	v_pk_fma_f32 v[232:233], v[124:125], v[124:125], v[232:233]
	global_load_dwordx2 v[186:187], v241, s[32:33] offset:3072
	global_load_dwordx2 v[188:189], v241, s[34:35] offset:3072
	s_waitcnt vmcnt(46)
	v_lshlrev_b32_e32 v228, 16, v126
	v_and_b32_e32 v229, 0xffff0000, v126
	v_lshlrev_b32_e32 v230, 16, v127
	v_and_b32_e32 v231, 0xffff0000, v127
	v_lshlrev_b32_e32 v126, 16, v128
	v_and_b32_e32 v127, 0xffff0000, v128
	v_lshlrev_b32_e32 v128, 16, v129
	v_and_b32_e32 v129, 0xffff0000, v129
	v_pk_add_f32 v[126:127], v[228:229], v[126:127]
	v_pk_add_f32 v[128:129], v[230:231], v[128:129]
	v_pk_fma_f32 v[232:233], v[126:127], v[126:127], v[232:233]
	v_pk_fma_f32 v[232:233], v[128:129], v[128:129], v[232:233]
	global_load_dwordx2 v[190:191], v241, s[32:33] offset:3584
	global_load_dwordx2 v[192:193], v241, s[34:35] offset:3584
	v_add_f32_e32 v217, v232, v233
	s_nop 1
	v_add_f32_dpp v217, v217, v217 row_shr:1 row_mask:0xf bank_mask:0xf bound_ctrl:1
	s_nop 1
	v_add_f32_dpp v217, v217, v217 row_shr:2 row_mask:0xf bank_mask:0xf bound_ctrl:1
	s_nop 1
	v_add_f32_dpp v217, v217, v217 row_shr:4 row_mask:0xf bank_mask:0xf bound_ctrl:1
	s_nop 1
	v_add_f32_dpp v217, v217, v217 row_shr:8 row_mask:0xf bank_mask:0xf bound_ctrl:1
	v_mov_b32_e32 v222, v195
	s_nop 1
	v_mov_b32_dpp v222, v217 row_bcast:15 row_mask:0xa bank_mask:0xf bound_ctrl:1
	v_add_f32_e32 v217, v217, v222
	v_mov_b32_e32 v222, v195
	s_nop 1
	v_mov_b32_dpp v222, v217 row_bcast:31 row_mask:0xc bank_mask:0xf bound_ctrl:1
	v_add_f32_e32 v217, v217, v222
	s_nop 1
	v_readlane_b32 s0, v217, 63
	s_nop 3
	v_fma_f32 v217, s0, v209, v202
	v_cmp_gt_f32_e32 vcc, s25, v217
	v_mul_f32_e32 v222, 0x4f800000, v217
	s_nop 1
	v_cndmask_b32_e32 v217, v217, v222, vcc
	v_sqrt_f32_e32 v222, v217
	s_nop 1
	v_add_u32_e32 v223, -1, v222
	v_fma_f32 v226, -v223, v222, v217
	v_cmp_ge_f32_e64 s[68:69], 0, v226
	v_add_u32_e32 v226, 1, v222
	s_nop 1
	v_cndmask_b32_e64 v223, v222, v223, s[68:69]
	v_fma_f32 v222, -v226, v222, v217
	v_cmp_lt_f32_e64 s[68:69], 0, v222
	s_nop 1
	v_cndmask_b32_e64 v222, v223, v226, s[68:69]
	v_mul_f32_e32 v223, 0x37800000, v222
	v_cndmask_b32_e32 v222, v222, v223, vcc
	v_cmp_class_f32_e32 vcc, v217, v203
	s_nop 1
	v_cndmask_b32_e32 v217, v222, v217, vcc
	v_div_scale_f32 v222, s[68:69], v217, v217, 1.0
	v_rcp_f32_e32 v223, v222
	s_nop 1
	v_fma_f32 v226, -v222, v223, 1.0
	v_fmac_f32_e32 v223, v226, v223
	v_div_scale_f32 v226, vcc, 1.0, v217, 1.0
	v_mul_f32_e32 v227, v226, v223
	v_fma_f32 v194, -v222, v227, v226
	v_fmac_f32_e32 v227, v194, v223
	v_fma_f32 v222, -v222, v227, v226
	s_nop 1
	v_div_fmas_f32 v222, v222, v223, v227
	v_div_fixup_f32 v234, v222, v217, 1.0
	s_waitcnt vmcnt(32)
	v_pk_mul_f32 v[66:67], v[66:67], v[234:235] op_sel_hi:[1,0]
	v_pk_mul_f32 v[68:69], v[68:69], v[234:235] op_sel_hi:[1,0]
	v_pk_mul_f32 v[66:67], v[2:3], v[66:67]
	v_pk_mul_f32 v[68:69], v[4:5], v[68:69]
	global_store_dwordx4 v236, v[66:69], s[36:37]
	v_pk_mul_f32 v[70:71], v[70:71], v[234:235] op_sel_hi:[1,0]
	v_pk_mul_f32 v[72:73], v[72:73], v[234:235] op_sel_hi:[1,0]
	v_pk_mul_f32 v[70:71], v[6:7], v[70:71]
	v_pk_mul_f32 v[72:73], v[8:9], v[72:73]
	global_store_dwordx4 v236, v[70:73], s[36:37] offset:1024
	v_pk_mul_f32 v[74:75], v[74:75], v[234:235] op_sel_hi:[1,0]
	v_pk_mul_f32 v[76:77], v[76:77], v[234:235] op_sel_hi:[1,0]
	v_pk_mul_f32 v[74:75], v[10:11], v[74:75]
	v_pk_mul_f32 v[76:77], v[12:13], v[76:77]
	global_store_dwordx4 v236, v[74:77], s[36:37] offset:2048
	v_pk_mul_f32 v[78:79], v[78:79], v[234:235] op_sel_hi:[1,0]
	v_pk_mul_f32 v[80:81], v[80:81], v[234:235] op_sel_hi:[1,0]
	v_pk_mul_f32 v[78:79], v[14:15], v[78:79]
	v_pk_mul_f32 v[80:81], v[16:17], v[80:81]
	global_store_dwordx4 v236, v[78:81], s[36:37] offset:3072
	v_pk_mul_f32 v[82:83], v[82:83], v[234:235] op_sel_hi:[1,0]
	v_pk_mul_f32 v[84:85], v[84:85], v[234:235] op_sel_hi:[1,0]
	v_pk_mul_f32 v[82:83], v[18:19], v[82:83]
	v_pk_mul_f32 v[84:85], v[20:21], v[84:85]
	global_store_dwordx4 v237, v[82:85], s[36:37]
	v_pk_mul_f32 v[86:87], v[86:87], v[234:235] op_sel_hi:[1,0]
	v_pk_mul_f32 v[88:89], v[88:89], v[234:235] op_sel_hi:[1,0]
	v_pk_mul_f32 v[86:87], v[22:23], v[86:87]
	v_pk_mul_f32 v[88:89], v[24:25], v[88:89]
	global_store_dwordx4 v237, v[86:89], s[36:37] offset:1024
	v_pk_mul_f32 v[90:91], v[90:91], v[234:235] op_sel_hi:[1,0]
	v_pk_mul_f32 v[92:93], v[92:93], v[234:235] op_sel_hi:[1,0]
	v_pk_mul_f32 v[90:91], v[26:27], v[90:91]
	v_pk_mul_f32 v[92:93], v[28:29], v[92:93]
	global_store_dwordx4 v237, v[90:93], s[36:37] offset:2048
	v_pk_mul_f32 v[94:95], v[94:95], v[234:235] op_sel_hi:[1,0]
	v_pk_mul_f32 v[96:97], v[96:97], v[234:235] op_sel_hi:[1,0]
	v_pk_mul_f32 v[94:95], v[30:31], v[94:95]
	v_pk_mul_f32 v[96:97], v[32:33], v[96:97]
	global_store_dwordx4 v237, v[94:97], s[36:37] offset:3072
	v_pk_mul_f32 v[98:99], v[98:99], v[234:235] op_sel_hi:[1,0]
	v_pk_mul_f32 v[100:101], v[100:101], v[234:235] op_sel_hi:[1,0]
	v_pk_mul_f32 v[98:99], v[34:35], v[98:99]
	v_pk_mul_f32 v[100:101], v[36:37], v[100:101]
	global_store_dwordx4 v238, v[98:101], s[36:37]
	v_pk_mul_f32 v[102:103], v[102:103], v[234:235] op_sel_hi:[1,0]
	v_pk_mul_f32 v[104:105], v[104:105], v[234:235] op_sel_hi:[1,0]
	v_pk_mul_f32 v[102:103], v[38:39], v[102:103]
	v_pk_mul_f32 v[104:105], v[40:41], v[104:105]
	global_store_dwordx4 v238, v[102:105], s[36:37] offset:1024
	v_pk_mul_f32 v[106:107], v[106:107], v[234:235] op_sel_hi:[1,0]
	v_pk_mul_f32 v[108:109], v[108:109], v[234:235] op_sel_hi:[1,0]
	v_pk_mul_f32 v[106:107], v[42:43], v[106:107]
	v_pk_mul_f32 v[108:109], v[44:45], v[108:109]
	global_store_dwordx4 v238, v[106:109], s[36:37] offset:2048
	v_pk_mul_f32 v[110:111], v[110:111], v[234:235] op_sel_hi:[1,0]
	v_pk_mul_f32 v[112:113], v[112:113], v[234:235] op_sel_hi:[1,0]
	v_pk_mul_f32 v[110:111], v[46:47], v[110:111]
	v_pk_mul_f32 v[112:113], v[48:49], v[112:113]
	global_store_dwordx4 v238, v[110:113], s[36:37] offset:3072
	v_pk_mul_f32 v[114:115], v[114:115], v[234:235] op_sel_hi:[1,0]
	v_pk_mul_f32 v[116:117], v[116:117], v[234:235] op_sel_hi:[1,0]
	v_pk_mul_f32 v[114:115], v[50:51], v[114:115]
	v_pk_mul_f32 v[116:117], v[52:53], v[116:117]
	global_store_dwordx4 v239, v[114:117], s[36:37]
	v_pk_mul_f32 v[118:119], v[118:119], v[234:235] op_sel_hi:[1,0]
	v_pk_mul_f32 v[120:121], v[120:121], v[234:235] op_sel_hi:[1,0]
	v_pk_mul_f32 v[118:119], v[54:55], v[118:119]
	v_pk_mul_f32 v[120:121], v[56:57], v[120:121]
	global_store_dwordx4 v239, v[118:121], s[36:37] offset:1024
	v_pk_mul_f32 v[122:123], v[122:123], v[234:235] op_sel_hi:[1,0]
	v_pk_mul_f32 v[124:125], v[124:125], v[234:235] op_sel_hi:[1,0]
	v_pk_mul_f32 v[122:123], v[58:59], v[122:123]
	v_pk_mul_f32 v[124:125], v[60:61], v[124:125]
	global_store_dwordx4 v239, v[122:125], s[36:37] offset:2048
	v_pk_mul_f32 v[126:127], v[126:127], v[234:235] op_sel_hi:[1,0]
	v_pk_mul_f32 v[128:129], v[128:129], v[234:235] op_sel_hi:[1,0]
	v_pk_mul_f32 v[126:127], v[62:63], v[126:127]
	v_pk_mul_f32 v[128:129], v[64:65], v[128:129]
	global_store_dwordx4 v239, v[126:129], s[36:37] offset:3072
	s_cmp_eq_u32 s39, 1
	s_cbranch_scc0 .Lph_loop
.Lph_done:
.LBB0_837:
	s_endpgm
